# w_ff1/w_ff2/w_in f32->bf16 conversion moved from the bandwidth-bound cscan phase into the G1 tile epilogues (one 32x64 item per wave per tile, quad-transposed coalesced stores)
# speedup vs baseline: 1.0050x; 1.0050x over previous
.LBB0_290:
	s_add_i32 s13, s59, -1
	s_mul_i32 s13, s13, s20
	s_add_i32 s13, s13, s16
	s_lshl_b32 s13, s13, 3
	s_add_i32 s13, s13, s21
	v_readlane_b32 s15, v254, 60
	s_mov_b32 s28, 0
	s_cmp_lt_u32 s13, 0x4000
	s_cbranch_scc0 .Lcv_win
	s_cmp_lt_u32 s13, 0x2000
	s_cbranch_scc0 .Lcv_ff2
	s_lshr_b32 s32, s13, 7
	s_and_b32 s41, s13, 0x7f
	v_mov_b32_e32 v192, 0x20548
	s_lshl_b32 s18, s32, 20
	s_lshl_b32 s19, s41, 8
	s_add_u32 s18, s18, s19
	s_lshl_b32 s22, s15, 26
	s_add_u32 s98, s18, s22
	s_lshl_b32 s26, s41, 18
	s_lshl_b32 s27, s32, 6
	s_add_u32 s26, s26, s27
	s_lshl_b32 s27, s15, 25
	s_add_u32 s26, s26, s27
	s_add_u32 s26, s26, 0x15400000
	s_mov_b32 s22, 0x8000
	s_mov_b32 s28, 12
	s_branch .Lcv_load
.Lcv_ff2:
	s_sub_u32 s13, s13, 0x2000
	s_lshr_b32 s32, s13, 5
	s_and_b32 s41, s13, 31
	v_mov_b32_e32 v192, 0x20558
	s_lshl_b32 s18, s32, 18
	s_lshl_b32 s19, s41, 8
	s_add_u32 s18, s18, s19
	s_lshl_b32 s22, s15, 26
	s_add_u32 s98, s18, s22
	s_lshl_b32 s26, s41, 20
	s_lshl_b32 s27, s32, 6
	s_add_u32 s26, s26, s27
	s_lshl_b32 s27, s15, 25
	s_add_u32 s26, s26, s27
	s_add_u32 s26, s26, 0x1d400000
	s_mov_b32 s22, 0x2000
	s_mov_b32 s28, 14
	s_branch .Lcv_load
.Lcv_win:
	s_cmp_eq_u32 s15, 3
	s_cbranch_scc1 .Lcv_none
	s_sub_u32 s13, s13, 0x4000
	s_mul_hi_u32 s32, s13, 0x1111112
	s_mul_i32 s41, s32, 0xf0
	s_sub_u32 s41, s13, s41
	v_mov_b32_e32 v192, 0x20458
	s_mul_i32 s18, s32, 0x1e0000
	s_lshl_b32 s19, s41, 8
	s_add_u32 s18, s18, s19
	s_add_i32 s19, s15, 1
	s_mul_i32 s22, s19, 0x7800000
	s_add_u32 s98, s18, s22
	s_lshl_b32 s26, s41, 18
	s_lshl_b32 s27, s32, 6
	s_add_u32 s26, s26, s27
	s_mul_i32 s27, s19, 0x3e00000
	s_add_u32 s26, s26, s27
	s_add_u32 s26, s26, 0x200000
	s_mov_b32 s22, 0xf000
	s_mov_b32 s28, 12
.Lcv_load:
	v_mov_b32_e32 v193, 0x20578
	ds_read_b64 v[194:195], v192
	ds_read_b64 v[196:197], v193
	v_lshlrev_b32_e32 v192, 2, v234
	s_waitcnt lgkmcnt(0)
	v_readfirstlane_b32 s18, v194
	v_readfirstlane_b32 s19, v195
	v_readfirstlane_b32 s32, v196
	v_readfirstlane_b32 s27, v197
	s_nop 3
	s_add_u32 s18, s18, s98
	s_addc_u32 s19, s19, 0
	s_add_u32 s26, s32, s26
	s_addc_u32 s27, s27, 0
	global_load_dword v160, v192, s[18:19] nt
	s_add_u32 s18, s18, s22
	s_addc_u32 s19, s19, 0
	global_load_dword v161, v192, s[18:19] nt
	s_add_u32 s18, s18, s22
	s_addc_u32 s19, s19, 0
	global_load_dword v162, v192, s[18:19] nt
	s_add_u32 s18, s18, s22
	s_addc_u32 s19, s19, 0
	global_load_dword v163, v192, s[18:19] nt
	s_add_u32 s18, s18, s22
	s_addc_u32 s19, s19, 0
	global_load_dword v164, v192, s[18:19] nt
	s_add_u32 s18, s18, s22
	s_addc_u32 s19, s19, 0
	global_load_dword v165, v192, s[18:19] nt
	s_add_u32 s18, s18, s22
	s_addc_u32 s19, s19, 0
	global_load_dword v166, v192, s[18:19] nt
	s_add_u32 s18, s18, s22
	s_addc_u32 s19, s19, 0
	global_load_dword v167, v192, s[18:19] nt
	s_add_u32 s18, s18, s22
	s_addc_u32 s19, s19, 0
	global_load_dword v168, v192, s[18:19] nt
	s_add_u32 s18, s18, s22
	s_addc_u32 s19, s19, 0
	global_load_dword v169, v192, s[18:19] nt
	s_add_u32 s18, s18, s22
	s_addc_u32 s19, s19, 0
	global_load_dword v170, v192, s[18:19] nt
	s_add_u32 s18, s18, s22
	s_addc_u32 s19, s19, 0
	global_load_dword v171, v192, s[18:19] nt
	s_add_u32 s18, s18, s22
	s_addc_u32 s19, s19, 0
	global_load_dword v172, v192, s[18:19] nt
	s_add_u32 s18, s18, s22
	s_addc_u32 s19, s19, 0
	global_load_dword v173, v192, s[18:19] nt
	s_add_u32 s18, s18, s22
	s_addc_u32 s19, s19, 0
	global_load_dword v174, v192, s[18:19] nt
	s_add_u32 s18, s18, s22
	s_addc_u32 s19, s19, 0
	global_load_dword v175, v192, s[18:19] nt
	s_add_u32 s18, s18, s22
	s_addc_u32 s19, s19, 0
	global_load_dword v176, v192, s[18:19] nt
	s_add_u32 s18, s18, s22
	s_addc_u32 s19, s19, 0
	global_load_dword v177, v192, s[18:19] nt
	s_add_u32 s18, s18, s22
	s_addc_u32 s19, s19, 0
	global_load_dword v178, v192, s[18:19] nt
	s_add_u32 s18, s18, s22
	s_addc_u32 s19, s19, 0
	global_load_dword v179, v192, s[18:19] nt
	s_add_u32 s18, s18, s22
	s_addc_u32 s19, s19, 0
	global_load_dword v180, v192, s[18:19] nt
	s_add_u32 s18, s18, s22
	s_addc_u32 s19, s19, 0
	global_load_dword v181, v192, s[18:19] nt
	s_add_u32 s18, s18, s22
	s_addc_u32 s19, s19, 0
	global_load_dword v182, v192, s[18:19] nt
	s_add_u32 s18, s18, s22
	s_addc_u32 s19, s19, 0
	global_load_dword v183, v192, s[18:19] nt
	s_add_u32 s18, s18, s22
	s_addc_u32 s19, s19, 0
	global_load_dword v184, v192, s[18:19] nt
	s_add_u32 s18, s18, s22
	s_addc_u32 s19, s19, 0
	global_load_dword v185, v192, s[18:19] nt
	s_add_u32 s18, s18, s22
	s_addc_u32 s19, s19, 0
	global_load_dword v186, v192, s[18:19] nt
	s_add_u32 s18, s18, s22
	s_addc_u32 s19, s19, 0
	global_load_dword v187, v192, s[18:19] nt
	s_add_u32 s18, s18, s22
	s_addc_u32 s19, s19, 0
	global_load_dword v188, v192, s[18:19] nt
	s_add_u32 s18, s18, s22
	s_addc_u32 s19, s19, 0
	global_load_dword v189, v192, s[18:19] nt
	s_add_u32 s18, s18, s22
	s_addc_u32 s19, s19, 0
	global_load_dword v190, v192, s[18:19] nt
	s_add_u32 s18, s18, s22
	s_addc_u32 s19, s19, 0
	global_load_dword v191, v192, s[18:19] nt

.LBB0_522:
	s_cmp_eq_u32 s28, 0
	s_cbranch_scc1 .Lcv_done
	s_waitcnt vmcnt(16)
	v_cvt_pk_bf16_f32 v196, v160, v161
	v_cvt_pk_bf16_f32 v197, v162, v163
	v_cvt_pk_bf16_f32 v198, v164, v165
	v_cvt_pk_bf16_f32 v199, v166, v167
	v_cvt_pk_bf16_f32 v200, v168, v169
	v_cvt_pk_bf16_f32 v201, v170, v171
	v_cvt_pk_bf16_f32 v202, v172, v173
	v_cvt_pk_bf16_f32 v203, v174, v175
	v_cvt_pk_bf16_f32 v204, v176, v177
	v_cvt_pk_bf16_f32 v205, v178, v179
	v_cvt_pk_bf16_f32 v206, v180, v181
	v_cvt_pk_bf16_f32 v207, v182, v183
	v_cvt_pk_bf16_f32 v208, v184, v185
	v_cvt_pk_bf16_f32 v209, v186, v187
	v_cvt_pk_bf16_f32 v210, v188, v189
	v_cvt_pk_bf16_f32 v211, v190, v191
	v_and_b32_e32 v192, 2, v234
	v_and_b32_e32 v193, 1, v234
	v_cmp_ne_u32_e64 s[18:19], 0, v192
	v_cmp_ne_u32_e64 s[100:101], 0, v193
	s_nop 3
	s_mov_b64 vcc, s[18:19]
	s_nop 1
	v_cndmask_b32_dpp v168, v196, v204, vcc quad_perm:[2,3,0,1] row_mask:0xf bank_mask:0xf
	v_cndmask_b32_dpp v169, v197, v205, vcc quad_perm:[2,3,0,1] row_mask:0xf bank_mask:0xf
	v_cndmask_b32_dpp v170, v198, v206, vcc quad_perm:[2,3,0,1] row_mask:0xf bank_mask:0xf
	v_cndmask_b32_dpp v171, v199, v207, vcc quad_perm:[2,3,0,1] row_mask:0xf bank_mask:0xf
	v_cndmask_b32_dpp v172, v200, v208, vcc quad_perm:[2,3,0,1] row_mask:0xf bank_mask:0xf
	v_cndmask_b32_dpp v173, v201, v209, vcc quad_perm:[2,3,0,1] row_mask:0xf bank_mask:0xf
	v_cndmask_b32_dpp v174, v202, v210, vcc quad_perm:[2,3,0,1] row_mask:0xf bank_mask:0xf
	v_cndmask_b32_dpp v175, v203, v211, vcc quad_perm:[2,3,0,1] row_mask:0xf bank_mask:0xf
	s_not_b64 vcc, s[18:19]
	s_nop 1
	v_cndmask_b32_dpp v160, v204, v196, vcc quad_perm:[2,3,0,1] row_mask:0xf bank_mask:0xf
	v_cndmask_b32_dpp v161, v205, v197, vcc quad_perm:[2,3,0,1] row_mask:0xf bank_mask:0xf
	v_cndmask_b32_dpp v162, v206, v198, vcc quad_perm:[2,3,0,1] row_mask:0xf bank_mask:0xf
	v_cndmask_b32_dpp v163, v207, v199, vcc quad_perm:[2,3,0,1] row_mask:0xf bank_mask:0xf
	v_cndmask_b32_dpp v164, v208, v200, vcc quad_perm:[2,3,0,1] row_mask:0xf bank_mask:0xf
	v_cndmask_b32_dpp v165, v209, v201, vcc quad_perm:[2,3,0,1] row_mask:0xf bank_mask:0xf
	v_cndmask_b32_dpp v166, v210, v202, vcc quad_perm:[2,3,0,1] row_mask:0xf bank_mask:0xf
	v_cndmask_b32_dpp v167, v211, v203, vcc quad_perm:[2,3,0,1] row_mask:0xf bank_mask:0xf
	s_mov_b64 vcc, s[100:101]
	s_nop 1
	v_cndmask_b32_dpp v180, v160, v164, vcc quad_perm:[1,0,3,2] row_mask:0xf bank_mask:0xf
	v_cndmask_b32_dpp v181, v161, v165, vcc quad_perm:[1,0,3,2] row_mask:0xf bank_mask:0xf
	v_cndmask_b32_dpp v182, v162, v166, vcc quad_perm:[1,0,3,2] row_mask:0xf bank_mask:0xf
	v_cndmask_b32_dpp v183, v163, v167, vcc quad_perm:[1,0,3,2] row_mask:0xf bank_mask:0xf
	v_cndmask_b32_dpp v188, v168, v172, vcc quad_perm:[1,0,3,2] row_mask:0xf bank_mask:0xf
	v_cndmask_b32_dpp v189, v169, v173, vcc quad_perm:[1,0,3,2] row_mask:0xf bank_mask:0xf
	v_cndmask_b32_dpp v190, v170, v174, vcc quad_perm:[1,0,3,2] row_mask:0xf bank_mask:0xf
	v_cndmask_b32_dpp v191, v171, v175, vcc quad_perm:[1,0,3,2] row_mask:0xf bank_mask:0xf
	s_not_b64 vcc, s[100:101]
	s_nop 1
	v_cndmask_b32_dpp v176, v164, v160, vcc quad_perm:[1,0,3,2] row_mask:0xf bank_mask:0xf
	v_cndmask_b32_dpp v177, v165, v161, vcc quad_perm:[1,0,3,2] row_mask:0xf bank_mask:0xf
	v_cndmask_b32_dpp v178, v166, v162, vcc quad_perm:[1,0,3,2] row_mask:0xf bank_mask:0xf
	v_cndmask_b32_dpp v179, v167, v163, vcc quad_perm:[1,0,3,2] row_mask:0xf bank_mask:0xf
	v_cndmask_b32_dpp v184, v172, v168, vcc quad_perm:[1,0,3,2] row_mask:0xf bank_mask:0xf
	v_cndmask_b32_dpp v185, v173, v169, vcc quad_perm:[1,0,3,2] row_mask:0xf bank_mask:0xf
	v_cndmask_b32_dpp v186, v174, v170, vcc quad_perm:[1,0,3,2] row_mask:0xf bank_mask:0xf
	v_cndmask_b32_dpp v187, v175, v171, vcc quad_perm:[1,0,3,2] row_mask:0xf bank_mask:0xf
	v_and_b32_e32 v192, 0x3c, v234
	v_and_b32_e32 v193, 3, v234
	v_lshlrev_b32_e32 v194, s28, v192
	v_lshl_add_u32 v194, v193, 4, v194
	v_mov_b32_e32 v195, 0
	s_lshl_b32 s98, 1, s28
	s_mov_b32 s99, 0
	v_lshl_add_u64 v[194:195], s[26:27], 0, v[194:195]
	global_store_dwordx4 v[194:195], v[176:179], off
	v_lshl_add_u64 v[194:195], v[194:195], 0, s[98:99]
	global_store_dwordx4 v[194:195], v[180:183], off
	v_lshl_add_u64 v[194:195], v[194:195], 0, s[98:99]
	global_store_dwordx4 v[194:195], v[184:187], off
	v_lshl_add_u64 v[194:195], v[194:195], 0, s[98:99]
	global_store_dwordx4 v[194:195], v[188:191], off
	s_mov_b32 s28, 0

.LBB0_1063:
	s_branch .LBB0_1069
	v_readlane_b32 s0, v254, 15
	s_mov_b32 s20, 0xf8000
	s_mov_b32 s24, 0x78000
	v_mov_b32_e32 v0, s0
	ds_read_b64 v[4:5], v0
	v_readlane_b32 s0, v254, 60
	v_readlane_b32 s1, v254, 61
	s_lshl_b64 s[0:1], s[0:1], 24
	s_cmpk_lt_i32 s36, 0x2000
	s_cselect_b64 s[2:3], -1, 0
	s_cmpk_gt_i32 s36, 0x1fff
	s_waitcnt lgkmcnt(0)
	v_readfirstlane_b32 s4, v4
	v_readfirstlane_b32 s5, v5
	s_mov_b32 s25, 0x80000
	s_mov_b32 s26, 0x90000
	s_mov_b32 s27, 0xa0000
	s_mov_b32 s34, 0xb0000
	s_mov_b32 s35, 0xf0000
	s_cbranch_scc1 .LBB0_1066
	s_lshl_b64 s[6:7], s[0:1], 2
	s_add_u32 s8, s4, s6
	s_addc_u32 s9, s5, s7
	s_lshl_b64 s[4:5], s[0:1], 1
	s_add_u32 s4, s12, s4
	s_addc_u32 s5, s13, s5
	s_add_u32 s4, s4, 0x15400000
	s_addc_u32 s5, s5, 0
	v_lshl_add_u32 v0, s36, 6, v150
	s_lshl_b32 s10, s37, 6
	s_mov_b32 s11, s36

.LBB0_1069:
	v_readlane_b32 s0, v254, 60
	s_cmp_eq_u32 s0, 3
	v_readlane_b32 s1, v254, 61
	s_cbranch_scc1 .LBB0_1110
	v_readlane_b32 s0, v254, 60
	s_add_i32 s16, s0, 1
	v_readlane_b32 s0, v253, 61
	v_readlane_b32 s1, v254, 61
	s_mul_i32 s1, s16, 0x3e00000
	v_mov_b32_e32 v0, s0
	ds_read_b64 v[4:5], v0
	s_mul_hi_u32 s0, s16, 0x3e00000
	s_mov_b32 s12, 0x78000
	s_mov_b32 s13, 0xf0000
	s_waitcnt lgkmcnt(0)
	v_readfirstlane_b32 s10, v4
	v_readfirstlane_b32 s11, v5
	s_add_u32 s1, s10, s1
	s_addc_u32 s2, s11, s0
	s_add_u32 s0, s1, 0x200000
	s_addc_u32 s1, s2, 0
	v_readlane_b32 s2, v254, 17
	s_cmpk_gt_i32 s36, 0x3bff
	s_nop 0
	v_mov_b32_e32 v0, s2
	ds_read_b64 v[4:5], v0
	s_waitcnt lgkmcnt(0)
	v_readfirstlane_b32 s2, v4
	v_readfirstlane_b32 s3, v5
	s_branch .LBB0_1073
	s_mul_i32 s4, s16, 0x7800000
	s_mul_hi_u32 s5, s16, 0x7800000
	s_add_u32 s4, s2, s4
	s_addc_u32 s5, s3, s5
	v_lshl_add_u32 v0, s36, 6, v150
	s_lshl_b32 s6, s37, 6
	s_mov_b32 s7, s36
